# v57: v53 + counted lgkmcnt waits (7/5/3/1/0) at the first consumers in the two 12-read in-proj MFMA sections instead of lgkmcnt(0) at the head
# speedup vs baseline: 1.0003x; 1.0003x over previous
; #define G_STAGE(bufoff, gbase, voff) do { _Pragma("unroll") for (int _i = 0; _i < 2; ++_i) \
;     __builtin_amdgcn_global_load_lds((const unsigned*)((const char*)(gbase) + (voff)[_i]), (LAS unsigned*)(lds + (bufoff) + ldsw + _i * 8192), 16, 0, 0); } while (0)
; #define G_LDA(dst, b, h) do { _Pragma("unroll") for (int m = 0; m < 4; ++m) _Pragma("unroll") for (int k = 0; k < 2; ++k) dst[m][k] = *(const LAS bf16x8*)(lds + G_SA(b, h) + aoff + m * 2048 + k * 1024); } while (0)
; #define G_LDB(dst, b, h) do { _Pragma("unroll") for (int n = 0; n < 2; ++n) _Pragma("unroll") for (int k = 0; k < 2; ++k) dst[n][k] = *(const LAS bf16x8*)(lds + G_SB(b, h) + boff + n * 2048 + k * 1024); } while (0)
; #define G_MMA(ai, bj, At, Bt) do { __builtin_amdgcn_s_setprio(1); _Pragma("unroll") for (int m = 0; m < 4; ++m) _Pragma("unroll") for (int n = 0; n < 2; ++n) _Pragma("unroll") for (int k = 0; k < 2; ++k) \
;     acc[ai][bj][m][n] = __builtin_amdgcn_mfma_f32_16x16x32_bf16(Bt[n][k], At[m][k], acc[ai][bj][m][n], 0, 0, 0); __builtin_amdgcn_s_setprio(0); } while (0)
; #define G_WAIT_V(n) asm volatile("s_waitcnt vmcnt(" #n ")" ::: "memory")
; #define G_WAIT_L(n) asm volatile("s_waitcnt lgkmcnt(" #n ")" ::: "memory")
; #define G_BAR __builtin_amdgcn_s_barrier()
; #define G_SCHED __builtin_amdgcn_sched_barrier(0)
; template <int GP> DI void gemm_phase(const Params& p, int l, int which, char* smem, int wv) {
;     ...
;       G_LDB(B0, 0, 0); G_SCHED; G_LDA(At, 0, 0); G_STAGE(G_SA(1, 1), a1 + hstep, voffA);
;       G_WAIT_L(8); G_BAR; G_WAIT_L(0); G_MMA(0, 0, At, B0); G_BAR; G_SCHED;
;       G_LDB(B1, 0, 1); G_STAGE(G_SB(0, 0), b2, vb0);
;       G_BAR; G_WAIT_L(0); G_MMA(0, 1, At, B1); G_BAR;
;       G_LDA(At, 0, 1); G_STAGE(G_SA(0, 0), a2, voffA);
;       G_BAR; G_WAIT_L(0); G_MMA(1, 0, At, B0); G_BAR; G_SCHED;
;       G_STAGE(G_SB(0, 1), b2, vb1);
;       G_WAIT_V(6); G_BAR; G_MMA(1, 1, At, B1); G_BAR;
;       G_LDB(B0, 1, 0); G_SCHED; G_LDA(At, 1, 0); G_STAGE(G_SA(0, 1), a2 + hstep, voffA);
;       G_WAIT_L(8); G_BAR; G_WAIT_L(0); G_MMA(0, 0, At, B0); G_BAR; G_SCHED;
;       G_LDB(B1, 1, 1); G_STAGE(G_SB(1, 0), b3, vb0);
;       G_BAR; G_WAIT_L(0); G_MMA(0, 1, At, B1); G_BAR;
;       G_LDA(At, 1, 1); G_STAGE(G_SA(1, 0), a3, voffA);
;       G_BAR; G_WAIT_L(0); G_MMA(1, 0, At, B0); G_BAR; G_SCHED;
;       G_STAGE(G_SB(1, 1), b3, vb1);
;       G_WAIT_V(6); G_BAR; G_MMA(1, 1, At, B1); G_BAR;
.Lkf_top:
	ds_read_b128 v[148:151], v228
	ds_read_b128 v[152:155], v228 offset:1024
	ds_read_b128 v[156:159], v228 offset:2048
	ds_read_b128 v[160:163], v228 offset:3072
	ds_read_b128 v[164:167], v211
	ds_read_b128 v[168:171], v211 offset:1024
	ds_read_b128 v[172:175], v211 offset:2048
	ds_read_b128 v[176:179], v211 offset:3072
	ds_read_b128 v[180:183], v211 offset:4096
	ds_read_b128 v[184:187], v211 offset:5120
	ds_read_b128 v[188:191], v211 offset:6144
	ds_read_b128 v[192:195], v211 offset:7168
	global_load_lds_dwordx4 v138, s[100:101]
	s_add_i32 m0, s23, 0xe000
	s_nop 0
	global_load_lds_dwordx4 v140, s[100:101]
	s_waitcnt lgkmcnt(8)
	s_barrier
	s_waitcnt lgkmcnt(7)
	v_mfma_f32_16x16x32_bf16 v[62:65], v[148:151], v[164:167], v[62:65]
	v_mfma_f32_16x16x32_bf16 v[58:61], v[156:159], v[164:167], v[58:61]
	s_mov_b32 m0, s25
	s_waitcnt lgkmcnt(5)
	v_mfma_f32_16x16x32_bf16 v[54:57], v[148:151], v[172:175], v[54:57]
	v_mfma_f32_16x16x32_bf16 v[50:53], v[156:159], v[172:175], v[50:53]
	s_waitcnt lgkmcnt(3)
	v_mfma_f32_16x16x32_bf16 v[46:49], v[148:151], v[180:183], v[46:49]
	v_mfma_f32_16x16x32_bf16 v[42:45], v[156:159], v[180:183], v[42:45]
	s_waitcnt lgkmcnt(1)
	v_mfma_f32_16x16x32_bf16 v[38:41], v[148:151], v[188:191], v[38:41]
	v_mfma_f32_16x16x32_bf16 v[34:37], v[156:159], v[188:191], v[34:37]
	v_mfma_f32_16x16x32_bf16 v[62:65], v[152:155], v[168:171], v[62:65]
	v_mfma_f32_16x16x32_bf16 v[58:61], v[160:163], v[168:171], v[58:61]
	v_mfma_f32_16x16x32_bf16 v[54:57], v[152:155], v[176:179], v[54:57]
	v_mfma_f32_16x16x32_bf16 v[50:53], v[160:163], v[176:179], v[50:53]
	v_mfma_f32_16x16x32_bf16 v[46:49], v[152:155], v[184:187], v[46:49]
	v_mfma_f32_16x16x32_bf16 v[42:45], v[160:163], v[184:187], v[42:45]
	s_waitcnt lgkmcnt(0)
	v_mfma_f32_16x16x32_bf16 v[38:41], v[152:155], v[192:195], v[38:41]
	v_mfma_f32_16x16x32_bf16 v[34:37], v[160:163], v[192:195], v[34:37]
	s_barrier
	ds_read_b128 v[196:199], v228 offset:16384
	ds_read_b128 v[200:203], v228 offset:17408
	ds_read_b128 v[204:207], v228 offset:18432
	ds_read_b128 v[238:241], v228 offset:19456
	global_load_lds_dwordx4 v0, s[6:7]
	s_mov_b32 m0, s58
	s_nop 0
	global_load_lds_dwordx4 v136, s[6:7]
	s_barrier
	s_waitcnt lgkmcnt(0)
	v_mfma_f32_16x16x32_bf16 v[30:33], v[196:199], v[164:167], v[30:33]
	v_mfma_f32_16x16x32_bf16 v[26:29], v[204:207], v[164:167], v[26:29]
	s_mov_b32 m0, s23
	v_mfma_f32_16x16x32_bf16 v[22:25], v[196:199], v[172:175], v[22:25]
	v_mfma_f32_16x16x32_bf16 v[18:21], v[204:207], v[172:175], v[18:21]
	v_mfma_f32_16x16x32_bf16 v[14:17], v[196:199], v[180:183], v[14:17]
	v_mfma_f32_16x16x32_bf16 v[10:13], v[204:207], v[180:183], v[10:13]
	v_mfma_f32_16x16x32_bf16 v[6:9], v[196:199], v[188:191], v[6:9]
	v_mfma_f32_16x16x32_bf16 v[2:5], v[204:207], v[188:191], v[2:5]
	v_mfma_f32_16x16x32_bf16 v[30:33], v[200:203], v[168:171], v[30:33]
	v_mfma_f32_16x16x32_bf16 v[26:29], v[238:241], v[168:171], v[26:29]
	v_mfma_f32_16x16x32_bf16 v[22:25], v[200:203], v[176:179], v[22:25]
	v_mfma_f32_16x16x32_bf16 v[18:21], v[238:241], v[176:179], v[18:21]
	v_mfma_f32_16x16x32_bf16 v[14:17], v[200:203], v[184:187], v[14:17]
	v_mfma_f32_16x16x32_bf16 v[10:13], v[238:241], v[184:187], v[10:13]
	v_mfma_f32_16x16x32_bf16 v[6:9], v[200:203], v[192:195], v[6:9]
	v_mfma_f32_16x16x32_bf16 v[2:5], v[238:241], v[192:195], v[2:5]
	s_barrier
	ds_read_b128 v[164:167], v211 offset:16384
	ds_read_b128 v[168:171], v211 offset:17408
	ds_read_b128 v[172:175], v211 offset:18432
	ds_read_b128 v[176:179], v211 offset:19456
	ds_read_b128 v[180:183], v211 offset:20480
	ds_read_b128 v[184:187], v211 offset:21504
	ds_read_b128 v[188:191], v211 offset:22528
	ds_read_b128 v[192:195], v211 offset:23552
	global_load_lds_dwordx4 v132, s[8:9]
	s_mov_b32 m0, s59
	s_nop 0
	global_load_lds_dwordx4 v134, s[8:9]
	s_barrier
	s_waitcnt lgkmcnt(0)
	v_mfma_f32_16x16x32_bf16 v[66:69], v[148:151], v[164:167], v[66:69]
	v_mfma_f32_16x16x32_bf16 v[70:73], v[156:159], v[164:167], v[70:73]
	s_mov_b32 m0, s60
	v_mfma_f32_16x16x32_bf16 v[74:77], v[148:151], v[172:175], v[74:77]
	v_mfma_f32_16x16x32_bf16 v[78:81], v[156:159], v[172:175], v[78:81]
	v_mfma_f32_16x16x32_bf16 v[82:85], v[148:151], v[180:183], v[82:85]
	v_mfma_f32_16x16x32_bf16 v[86:89], v[156:159], v[180:183], v[86:89]
	v_mfma_f32_16x16x32_bf16 v[90:93], v[148:151], v[188:191], v[90:93]
	v_mfma_f32_16x16x32_bf16 v[94:97], v[156:159], v[188:191], v[94:97]
	v_mfma_f32_16x16x32_bf16 v[66:69], v[152:155], v[168:171], v[66:69]
	v_mfma_f32_16x16x32_bf16 v[70:73], v[160:163], v[168:171], v[70:73]
	v_mfma_f32_16x16x32_bf16 v[74:77], v[152:155], v[176:179], v[74:77]
	v_mfma_f32_16x16x32_bf16 v[78:81], v[160:163], v[176:179], v[78:81]
	v_mfma_f32_16x16x32_bf16 v[82:85], v[152:155], v[184:187], v[82:85]
	v_mfma_f32_16x16x32_bf16 v[86:89], v[160:163], v[184:187], v[86:89]
	v_mfma_f32_16x16x32_bf16 v[90:93], v[152:155], v[192:195], v[90:93]
	v_mfma_f32_16x16x32_bf16 v[94:97], v[160:163], v[192:195], v[94:97]
	s_barrier
	global_load_lds_dwordx4 v130, s[6:7]
	s_mov_b32 m0, s61
	s_nop 0
	global_load_lds_dwordx4 v142, s[6:7]
	s_waitcnt vmcnt(6)
	s_barrier
; #define G_STAGE(bufoff, gbase, voff) do { _Pragma("unroll") for (int _i = 0; _i < 2; ++_i) \
;     __builtin_amdgcn_global_load_lds((const unsigned*)((const char*)(gbase) + (voff)[_i]), (LAS unsigned*)(lds + (bufoff) + ldsw + _i * 8192), 16, 0, 0); } while (0)
; #define G_LDA(dst, b, h) do { _Pragma("unroll") for (int m = 0; m < 4; ++m) _Pragma("unroll") for (int k = 0; k < 2; ++k) dst[m][k] = *(const LAS bf16x8*)(lds + G_SA(b, h) + aoff + m * 2048 + k * 1024); } while (0)
; #define G_LDB(dst, b, h) do { _Pragma("unroll") for (int n = 0; n < 2; ++n) _Pragma("unroll") for (int k = 0; k < 2; ++k) dst[n][k] = *(const LAS bf16x8*)(lds + G_SB(b, h) + boff + n * 2048 + k * 1024); } while (0)
; #define G_MMA(ai, bj, At, Bt) do { __builtin_amdgcn_s_setprio(1); _Pragma("unroll") for (int m = 0; m < 4; ++m) _Pragma("unroll") for (int n = 0; n < 2; ++n) _Pragma("unroll") for (int k = 0; k < 2; ++k) \
;     acc[ai][bj][m][n] = __builtin_amdgcn_mfma_f32_16x16x32_bf16(Bt[n][k], At[m][k], acc[ai][bj][m][n], 0, 0, 0); __builtin_amdgcn_s_setprio(0); } while (0)
; #define G_WAIT_V(n) asm volatile("s_waitcnt vmcnt(" #n ")" ::: "memory")
; #define G_WAIT_L(n) asm volatile("s_waitcnt lgkmcnt(" #n ")" ::: "memory")
; #define G_BAR __builtin_amdgcn_s_barrier()
; #define G_SCHED __builtin_amdgcn_sched_barrier(0)
; template <int GP> DI void gemm_phase(const Params& p, int l, int which, char* smem, int wv) {
;     ...
;       G_LDB(B0, 0, 0); G_SCHED; G_LDA(At, 0, 0); G_STAGE(G_SA(1, 1), a1 + hstep, voffA);
;       G_WAIT_L(8); G_BAR; G_WAIT_L(0); G_MMA(0, 0, At, B0); G_BAR; G_SCHED;
;       G_LDB(B1, 0, 1); G_STAGE(G_SB(0, 0), b2, vb0);
;       G_BAR; G_WAIT_L(0); G_MMA(0, 1, At, B1); G_BAR;
;       G_LDA(At, 0, 1); G_STAGE(G_SA(0, 0), a2, voffA);
;       G_BAR; G_WAIT_L(0); G_MMA(1, 0, At, B0); G_BAR; G_SCHED;
;       G_STAGE(G_SB(0, 1), b2, vb1);
;       G_WAIT_V(6); G_BAR; G_MMA(1, 1, At, B1); G_BAR;
;       G_LDB(B0, 1, 0); G_SCHED; G_LDA(At, 1, 0); G_STAGE(G_SA(0, 1), a2 + hstep, voffA);
;       G_WAIT_L(8); G_BAR; G_WAIT_L(0); G_MMA(0, 0, At, B0); G_BAR; G_SCHED;
;       G_LDB(B1, 1, 1); G_STAGE(G_SB(1, 0), b3, vb0);
;       G_BAR; G_WAIT_L(0); G_MMA(0, 1, At, B1); G_BAR;
;       G_LDA(At, 1, 1); G_STAGE(G_SA(1, 0), a3, voffA);
;       G_BAR; G_WAIT_L(0); G_MMA(1, 0, At, B0); G_BAR; G_SCHED;
;       G_STAGE(G_SB(1, 1), b3, vb1);
;       G_WAIT_V(6); G_BAR; G_MMA(1, 1, At, B1); G_BAR;
	v_mfma_f32_16x16x32_bf16 v[98:101], v[196:199], v[164:167], v[98:101]
	v_mfma_f32_16x16x32_bf16 v[102:105], v[204:207], v[164:167], v[102:105]
	s_add_u32 s100, s8, 0x80000
	s_addc_u32 s101, s9, 0
	s_mov_b32 m0, s62
	v_mfma_f32_16x16x32_bf16 v[106:109], v[196:199], v[172:175], v[106:109]
	v_mfma_f32_16x16x32_bf16 v[110:113], v[204:207], v[172:175], v[110:113]
	v_mfma_f32_16x16x32_bf16 v[114:117], v[196:199], v[180:183], v[114:117]
	v_mfma_f32_16x16x32_bf16 v[118:121], v[204:207], v[180:183], v[118:121]
	v_mfma_f32_16x16x32_bf16 v[122:125], v[196:199], v[188:191], v[122:125]
	v_mfma_f32_16x16x32_bf16 v[126:129], v[204:207], v[188:191], v[126:129]
	v_mfma_f32_16x16x32_bf16 v[98:101], v[200:203], v[168:171], v[98:101]
	v_mfma_f32_16x16x32_bf16 v[102:105], v[238:241], v[168:171], v[102:105]
	v_mfma_f32_16x16x32_bf16 v[106:109], v[200:203], v[176:179], v[106:109]
	v_mfma_f32_16x16x32_bf16 v[110:113], v[238:241], v[176:179], v[110:113]
	v_mfma_f32_16x16x32_bf16 v[114:117], v[200:203], v[184:187], v[114:117]
	v_mfma_f32_16x16x32_bf16 v[118:121], v[238:241], v[184:187], v[118:121]
	v_mfma_f32_16x16x32_bf16 v[122:125], v[200:203], v[192:195], v[122:125]
	v_mfma_f32_16x16x32_bf16 v[126:129], v[238:241], v[192:195], v[126:129]
	s_barrier
	ds_read_b128 v[148:151], v228 offset:32768
	ds_read_b128 v[152:155], v228 offset:33792
	ds_read_b128 v[156:159], v228 offset:34816
	ds_read_b128 v[160:163], v228 offset:35840
	ds_read_b128 v[164:167], v211 offset:32768
	ds_read_b128 v[168:171], v211 offset:33792
	ds_read_b128 v[172:175], v211 offset:34816
	ds_read_b128 v[176:179], v211 offset:35840
	ds_read_b128 v[180:183], v211 offset:36864
	ds_read_b128 v[184:187], v211 offset:37888
	ds_read_b128 v[188:191], v211 offset:38912
	ds_read_b128 v[192:195], v211 offset:39936
	global_load_lds_dwordx4 v132, s[100:101]
	s_mov_b32 m0, s63
	s_nop 0
	global_load_lds_dwordx4 v134, s[100:101]
	s_waitcnt lgkmcnt(8)
	s_barrier
	s_waitcnt lgkmcnt(7)
	v_mfma_f32_16x16x32_bf16 v[62:65], v[148:151], v[164:167], v[62:65]
	v_mfma_f32_16x16x32_bf16 v[58:61], v[156:159], v[164:167], v[58:61]
	s_mov_b32 m0, s21
	s_add_u32 s100, s6, s16
	s_addc_u32 s101, s7, s17
	s_waitcnt lgkmcnt(5)
	v_mfma_f32_16x16x32_bf16 v[54:57], v[148:151], v[172:175], v[54:57]
	v_mfma_f32_16x16x32_bf16 v[50:53], v[156:159], v[172:175], v[50:53]
	s_waitcnt lgkmcnt(3)
	v_mfma_f32_16x16x32_bf16 v[46:49], v[148:151], v[180:183], v[46:49]
	v_mfma_f32_16x16x32_bf16 v[42:45], v[156:159], v[180:183], v[42:45]
	s_waitcnt lgkmcnt(1)
	v_mfma_f32_16x16x32_bf16 v[38:41], v[148:151], v[188:191], v[38:41]
	v_mfma_f32_16x16x32_bf16 v[34:37], v[156:159], v[188:191], v[34:37]
	v_mfma_f32_16x16x32_bf16 v[62:65], v[152:155], v[168:171], v[62:65]
	v_mfma_f32_16x16x32_bf16 v[58:61], v[160:163], v[168:171], v[58:61]
	v_mfma_f32_16x16x32_bf16 v[54:57], v[152:155], v[176:179], v[54:57]
	v_mfma_f32_16x16x32_bf16 v[50:53], v[160:163], v[176:179], v[50:53]
	v_mfma_f32_16x16x32_bf16 v[46:49], v[152:155], v[184:187], v[46:49]
	v_mfma_f32_16x16x32_bf16 v[42:45], v[160:163], v[184:187], v[42:45]
	s_waitcnt lgkmcnt(0)
	v_mfma_f32_16x16x32_bf16 v[38:41], v[152:155], v[192:195], v[38:41]
	v_mfma_f32_16x16x32_bf16 v[34:37], v[160:163], v[192:195], v[34:37]
	s_barrier
	ds_read_b128 v[196:199], v228 offset:49152
	ds_read_b128 v[200:203], v228 offset:50176
	ds_read_b128 v[204:207], v228 offset:51200
	ds_read_b128 v[238:241], v228 offset:52224
	global_load_lds_dwordx4 v0, s[100:101]
	s_mov_b32 m0, s64
	s_nop 0
	global_load_lds_dwordx4 v136, s[100:101]
	s_barrier
; #define G_STAGE(bufoff, gbase, voff) do { _Pragma("unroll") for (int _i = 0; _i < 2; ++_i) \
;     __builtin_amdgcn_global_load_lds((const unsigned*)((const char*)(gbase) + (voff)[_i]), (LAS unsigned*)(lds + (bufoff) + ldsw + _i * 8192), 16, 0, 0); } while (0)
; #define G_LDA(dst, b, h) do { _Pragma("unroll") for (int m = 0; m < 4; ++m) _Pragma("unroll") for (int k = 0; k < 2; ++k) dst[m][k] = *(const LAS bf16x8*)(lds + G_SA(b, h) + aoff + m * 2048 + k * 1024); } while (0)
; #define G_LDB(dst, b, h) do { _Pragma("unroll") for (int n = 0; n < 2; ++n) _Pragma("unroll") for (int k = 0; k < 2; ++k) dst[n][k] = *(const LAS bf16x8*)(lds + G_SB(b, h) + boff + n * 2048 + k * 1024); } while (0)
; #define G_WAIT_V(n) asm volatile("s_waitcnt vmcnt(" #n ")" ::: "memory")
; #define G_BAR __builtin_amdgcn_s_barrier()
; template <int GP> DI void gemm_phase(const Params& p, int l, int which, char* smem, int wv) {
;     ...
;     for (int t = 0; t < cnk; t += 2) {
;       const bool last = (t == cnk - 2);
;       const char* a1 = cA + (size_t)(t + 1) * kstep;
;       const char* a2 = last ? nA : cA + (size_t)(t + 2) * kstep; const char* b2 = last ? nB : cB + (size_t)(t + 2) * kstep;
;       const char* a3 = a2 + kstep; const char* b3 = b2 + kstep;
;       if (last) {
; #pragma unroll
;         for (int i = 0; i < 2; ++i) { vb0[i] = voffB(i, 0, n32); vb1[i] = voffB(i, 1, n32); }
;       }
;       G_LDB(B0, 0, 0); G_SCHED; G_LDA(At, 0, 0); G_STAGE(G_SA(1, 1), a1 + hstep, voffA);
;       G_WAIT_L(8); G_BAR; G_WAIT_L(0); G_MMA(0, 0, At, B0); G_BAR; G_SCHED;
;       G_LDB(B1, 0, 1); G_STAGE(G_SB(0, 0), b2, vb0);
;       G_BAR; G_WAIT_L(0); G_MMA(0, 1, At, B1); G_BAR;
;       G_LDA(At, 0, 1); G_STAGE(G_SA(0, 0), a2, voffA);
;       G_BAR; G_WAIT_L(0); G_MMA(1, 0, At, B0); G_BAR; G_SCHED;
;       G_STAGE(G_SB(0, 1), b2, vb1);
;       G_WAIT_V(6); G_BAR; G_MMA(1, 1, At, B1); G_BAR;
;       G_LDB(B0, 1, 0); G_SCHED; G_LDA(At, 1, 0); G_STAGE(G_SA(0, 1), a2 + hstep, voffA);
;       G_WAIT_L(8); G_BAR; G_WAIT_L(0); G_MMA(0, 0, At, B0); G_BAR; G_SCHED;
;       G_LDB(B1, 1, 1); G_STAGE(G_SB(1, 0), b3, vb0);
;       G_BAR; G_WAIT_L(0); G_MMA(0, 1, At, B1); G_BAR;
;       G_LDA(At, 1, 1); G_STAGE(G_SA(1, 0), a3, voffA);
;       G_BAR; G_WAIT_L(0); G_MMA(1, 0, At, B0); G_BAR; G_SCHED;
;       G_STAGE(G_SB(1, 1), b3, vb1);
;       G_WAIT_V(6); G_BAR; G_MMA(1, 1, At, B1); G_BAR;
	s_waitcnt lgkmcnt(0)
	v_mfma_f32_16x16x32_bf16 v[30:33], v[196:199], v[164:167], v[30:33]
	v_mfma_f32_16x16x32_bf16 v[26:29], v[204:207], v[164:167], v[26:29]
	s_mov_b32 m0, s65
	s_add_u32 s100, s8, s16
	s_addc_u32 s101, s9, s17
	v_mfma_f32_16x16x32_bf16 v[22:25], v[196:199], v[172:175], v[22:25]
	v_mfma_f32_16x16x32_bf16 v[18:21], v[204:207], v[172:175], v[18:21]
	v_mfma_f32_16x16x32_bf16 v[14:17], v[196:199], v[180:183], v[14:17]
	v_mfma_f32_16x16x32_bf16 v[10:13], v[204:207], v[180:183], v[10:13]
	v_mfma_f32_16x16x32_bf16 v[6:9], v[196:199], v[188:191], v[6:9]
	v_mfma_f32_16x16x32_bf16 v[2:5], v[204:207], v[188:191], v[2:5]
	v_mfma_f32_16x16x32_bf16 v[30:33], v[200:203], v[168:171], v[30:33]
	v_mfma_f32_16x16x32_bf16 v[26:29], v[238:241], v[168:171], v[26:29]
	v_mfma_f32_16x16x32_bf16 v[22:25], v[200:203], v[176:179], v[22:25]
	v_mfma_f32_16x16x32_bf16 v[18:21], v[238:241], v[176:179], v[18:21]
	v_mfma_f32_16x16x32_bf16 v[14:17], v[200:203], v[184:187], v[14:17]
	v_mfma_f32_16x16x32_bf16 v[10:13], v[238:241], v[184:187], v[10:13]
	v_mfma_f32_16x16x32_bf16 v[6:9], v[200:203], v[192:195], v[6:9]
	v_mfma_f32_16x16x32_bf16 v[2:5], v[238:241], v[192:195], v[2:5]
	s_barrier
	ds_read_b128 v[164:167], v211 offset:49152
	ds_read_b128 v[168:171], v211 offset:50176
	ds_read_b128 v[172:175], v211 offset:51200
	ds_read_b128 v[176:179], v211 offset:52224
	ds_read_b128 v[180:183], v211 offset:53248
	ds_read_b128 v[184:187], v211 offset:54272
	ds_read_b128 v[188:191], v211 offset:55296
	ds_read_b128 v[192:195], v211 offset:56320
	global_load_lds_dwordx4 v132, s[100:101]
	s_mov_b32 m0, s66
	s_nop 0
	global_load_lds_dwordx4 v134, s[100:101]
	s_barrier
	s_waitcnt lgkmcnt(0)
	v_mfma_f32_16x16x32_bf16 v[66:69], v[148:151], v[164:167], v[66:69]
	v_mfma_f32_16x16x32_bf16 v[70:73], v[156:159], v[164:167], v[70:73]
	s_mov_b32 m0, s67
	s_add_u32 s100, s6, s16
	s_addc_u32 s101, s7, s17
	v_mfma_f32_16x16x32_bf16 v[74:77], v[148:151], v[172:175], v[74:77]
	v_mfma_f32_16x16x32_bf16 v[78:81], v[156:159], v[172:175], v[78:81]
	v_mfma_f32_16x16x32_bf16 v[82:85], v[148:151], v[180:183], v[82:85]
	v_mfma_f32_16x16x32_bf16 v[86:89], v[156:159], v[180:183], v[86:89]
	v_mfma_f32_16x16x32_bf16 v[90:93], v[148:151], v[188:191], v[90:93]
	v_mfma_f32_16x16x32_bf16 v[94:97], v[156:159], v[188:191], v[94:97]
	v_mfma_f32_16x16x32_bf16 v[66:69], v[152:155], v[168:171], v[66:69]
	v_mfma_f32_16x16x32_bf16 v[70:73], v[160:163], v[168:171], v[70:73]
	v_mfma_f32_16x16x32_bf16 v[74:77], v[152:155], v[176:179], v[74:77]
	v_mfma_f32_16x16x32_bf16 v[78:81], v[160:163], v[176:179], v[78:81]
	v_mfma_f32_16x16x32_bf16 v[82:85], v[152:155], v[184:187], v[82:85]
	v_mfma_f32_16x16x32_bf16 v[86:89], v[160:163], v[184:187], v[86:89]
	v_mfma_f32_16x16x32_bf16 v[90:93], v[152:155], v[192:195], v[90:93]
	v_mfma_f32_16x16x32_bf16 v[94:97], v[160:163], v[192:195], v[94:97]
	s_barrier
	global_load_lds_dwordx4 v130, s[100:101]
	s_mov_b32 m0, s68
	s_nop 0
	global_load_lds_dwordx4 v142, s[100:101]
	s_waitcnt vmcnt(6)
	s_barrier
	v_mfma_f32_16x16x32_bf16 v[98:101], v[196:199], v[164:167], v[98:101]
	v_mfma_f32_16x16x32_bf16 v[102:105], v[204:207], v[164:167], v[102:105]
	s_add_i32 m0, s23, 0xc000
	v_mfma_f32_16x16x32_bf16 v[106:109], v[196:199], v[172:175], v[106:109]
	v_mfma_f32_16x16x32_bf16 v[110:113], v[204:207], v[172:175], v[110:113]
	v_mfma_f32_16x16x32_bf16 v[114:117], v[196:199], v[180:183], v[114:117]
	v_mfma_f32_16x16x32_bf16 v[118:121], v[204:207], v[180:183], v[118:121]
	v_mfma_f32_16x16x32_bf16 v[122:125], v[196:199], v[188:191], v[122:125]
	v_mfma_f32_16x16x32_bf16 v[126:129], v[204:207], v[188:191], v[126:129]
	v_mfma_f32_16x16x32_bf16 v[98:101], v[200:203], v[168:171], v[98:101]
	s_add_i32 s50, s50, 2
	s_add_u32 s2, s2, 0x100
	s_addc_u32 s3, s3, 0
	v_mfma_f32_16x16x32_bf16 v[102:105], v[238:241], v[168:171], v[102:105]
	s_add_u32 s8, s28, s2
	s_addc_u32 s9, s29, s3
	v_mfma_f32_16x16x32_bf16 v[106:109], v[200:203], v[176:179], v[106:109]
	s_add_u32 s100, s8, 0x80080
	s_addc_u32 s101, s9, 0
	v_mfma_f32_16x16x32_bf16 v[110:113], v[238:241], v[176:179], v[110:113]
	s_add_u32 s8, s8, 0x100
	s_addc_u32 s9, s9, 0
	v_mfma_f32_16x16x32_bf16 v[114:117], v[200:203], v[184:187], v[114:117]
	s_add_u32 s6, s74, s2
	s_addc_u32 s7, s75, s3
	s_branch .Lkf_rot
